# P7 K-loop: leading half stages all LDS-DMA pieces (own + wave+4), retires after the MFMA blocks; trailing half issues no loads
# baseline (speedup 1.0000x reference)
; #define PG8_STAGE(bufoff, gbase, voff) do { _Pragma("unroll") for (int _i = 0; _i < 2; ++_i) \
;         __builtin_amdgcn_global_load_lds((const unsigned*)((const char*)(gbase) + (voff)[_i]), (PG8_LAS unsigned*)(lds + (bufoff) + ldsw + _i * 8192), 16, 0, 0); } while (0)
; #define PG8_LDA(dst, b, h) do { _Pragma("unroll") for (int m = 0; m < 4; ++m) _Pragma("unroll") for (int k = 0; k < 2; ++k) dst[m][k] = *(const PG8_LAS bf16x8*)(lds + PG8_SA(b, h) + aoff + m * 2048 + k * 1024); } while (0)
; #define PG8_LDB(dst, b, h) do { _Pragma("unroll") for (int n = 0; n < 2; ++n) _Pragma("unroll") for (int k = 0; k < 2; ++k) dst[n][k] = *(const PG8_LAS bf16x8*)(lds + PG8_SB(b, h) + boff + n * 2048 + k * 1024); } while (0)
; #define PG8_MMA(ai, bj, At, Bt) do { __builtin_amdgcn_s_setprio(1); _Pragma("unroll") for (int m = 0; m < 4; ++m) _Pragma("unroll") for (int n = 0; n < 2; ++n) _Pragma("unroll") for (int k = 0; k < 2; ++k) \
;         acc[ai][bj][m][n] = __builtin_amdgcn_mfma_f32_16x16x32_bf16(Bt[n][k], At[m][k], acc[ai][bj][m][n], 0, 0, 0); __builtin_amdgcn_s_setprio(0); } while (0)
; #define PG8_WAIT_V(n) asm volatile("s_waitcnt vmcnt(" #n ")" ::: "memory")
; #define PG8_WAIT_L(n) asm volatile("s_waitcnt lgkmcnt(" #n ")" ::: "memory")
; #define PG8_BAR __builtin_amdgcn_s_barrier()
; #define PG8_SCHED __builtin_amdgcn_sched_barrier(0)
; template <class Epi, class Sched, bool ALIGN_EPI = false, bool SP2 = false>
; __device__ __forceinline__ void gemm_phase(PG8_LAS unsigned char* lds, const Gemm g, const Sched& S, const Epi& E, int tid_in) {
;     ...
;             PG8_LDB(B0, 0, 0); PG8_LDB(B1, 0, 1); PG8_SCHED; PG8_LDA(At, 0, 0); PG8_STAGE(PG8_SA(1, 1), a1 + hstep, voffA);
;             PG8_WAIT_V(8); PG8_WAIT_L(0); PG8_BAR; PG8_MMA(0, 0, At, B0); PG8_MMA(0, 1, At, B1); PG8_BAR; PG8_SCHED;
;             PG8_LDA(At, 0, 1); PG8_STAGE(PG8_SB(0, 0), b2, voffB); PG8_STAGE(PG8_SB(0, 1), b2 + hstep, voffB); PG8_STAGE(PG8_SA(0, 0), a2, voffA);
;             PG8_WAIT_V(8); PG8_WAIT_L(0); PG8_BAR; PG8_MMA(1, 0, At, B0); PG8_MMA(1, 1, At, B1); PG8_BAR; PG8_SCHED;
.LBB0_1551:
	s_mov_b64 vcc, s[8:9]
	s_mov_b32 s68, 0x40000
	s_mov_b32 s69, 0
	s_mov_b32 s70, 0xfffc0000
	s_mov_b32 s71, -1
	ds_read_b128 v[150:153], v147
	ds_read_b128 v[154:157], v147 offset:1024
	ds_read_b128 v[158:161], v147 offset:2048
	ds_read_b128 v[162:165], v147 offset:3072
	ds_read_b128 v[166:169], v148
	ds_read_b128 v[170:173], v148 offset:1024
	ds_read_b128 v[174:177], v148 offset:2048
	ds_read_b128 v[178:181], v148 offset:3072
	s_add_u32 s34, s30, 0xfff00080
	s_addc_u32 s35, s31, -1
	s_cmp_eq_u32 s60, 60
	s_cselect_b32 s37, s21, s35
	s_cselect_b32 s36, s56, s34
	s_cselect_b32 s35, s19, s59
	s_cselect_b32 s34, s57, s58
	v_lshl_add_u64 v[142:143], s[30:31], 0, v[136:137]
	s_add_i32 m0, s29, 0xc000
	ds_read_b128 v[182:185], v149
	ds_read_b128 v[186:189], v149 offset:1024
	ds_read_b128 v[190:193], v149 offset:2048
	ds_read_b128 v[194:197], v149 offset:3072
	ds_read_b128 v[198:201], v149 offset:4096
	ds_read_b128 v[202:205], v149 offset:5120
	ds_read_b128 v[206:209], v149 offset:6144
	ds_read_b128 v[210:213], v149 offset:7168
	s_cbranch_vccz .Ldl_0
	global_load_lds_dwordx4 v[142:143], off
	v_lshl_add_u64 v[142:143], v[142:143], 0, s[68:69]
	s_add_i32 m0, m0, 0x1000
	s_nop 0
	global_load_lds_dwordx4 v[142:143], off
	v_lshl_add_u64 v[142:143], v[142:143], 0, s[70:71]
.Ldl_0:
	v_lshl_add_u64 v[142:143], s[30:31], 0, v[138:139]
	s_add_i32 m0, s29, 0xe000
	s_nop 0
	s_cbranch_vccz .Ldl_1
	global_load_lds_dwordx4 v[142:143], off
	v_lshl_add_u64 v[142:143], v[142:143], 0, s[68:69]
	s_add_i32 m0, m0, 0x1000
	s_nop 0
	global_load_lds_dwordx4 v[142:143], off
	v_lshl_add_u64 v[142:143], v[142:143], 0, s[70:71]
.Ldl_1:
	s_cbranch_vccnz .Ldw_0
	s_waitcnt vmcnt(0)
.Ldw_0:
	s_waitcnt lgkmcnt(0)
	s_barrier
	s_setprio 1
	s_waitcnt lgkmcnt(0)
	v_mfma_f32_16x16x32_bf16 v[124:127], v[150:153], v[182:185], v[124:127]
	v_mfma_f32_16x16x32_bf16 v[120:123], v[158:161], v[182:185], v[120:123]
	v_mfma_f32_16x16x32_bf16 v[112:115], v[150:153], v[190:193], v[112:115]
	v_mfma_f32_16x16x32_bf16 v[104:107], v[158:161], v[190:193], v[104:107]
	v_mfma_f32_16x16x32_bf16 v[96:99], v[150:153], v[198:201], v[96:99]
	v_mfma_f32_16x16x32_bf16 v[88:91], v[158:161], v[198:201], v[88:91]
	v_mfma_f32_16x16x32_bf16 v[80:83], v[150:153], v[206:209], v[80:83]
	v_mfma_f32_16x16x32_bf16 v[72:75], v[158:161], v[206:209], v[72:75]
	v_mfma_f32_16x16x32_bf16 v[124:127], v[154:157], v[186:189], v[124:127]
	v_mfma_f32_16x16x32_bf16 v[120:123], v[162:165], v[186:189], v[120:123]
	v_mfma_f32_16x16x32_bf16 v[112:115], v[154:157], v[194:197], v[112:115]
	v_mfma_f32_16x16x32_bf16 v[104:107], v[162:165], v[194:197], v[104:107]
	v_mfma_f32_16x16x32_bf16 v[96:99], v[154:157], v[202:205], v[96:99]
	v_mfma_f32_16x16x32_bf16 v[88:91], v[162:165], v[202:205], v[88:91]
	v_mfma_f32_16x16x32_bf16 v[80:83], v[154:157], v[210:213], v[80:83]
	v_mfma_f32_16x16x32_bf16 v[72:75], v[162:165], v[210:213], v[72:75]
	s_setprio 0
	s_setprio 1
	v_mfma_f32_16x16x32_bf16 v[116:119], v[166:169], v[182:185], v[116:119]
	v_mfma_f32_16x16x32_bf16 v[108:111], v[174:177], v[182:185], v[108:111]
	v_mfma_f32_16x16x32_bf16 v[100:103], v[166:169], v[190:193], v[100:103]
	v_mfma_f32_16x16x32_bf16 v[92:95], v[174:177], v[190:193], v[92:95]
	v_mfma_f32_16x16x32_bf16 v[84:87], v[166:169], v[198:201], v[84:87]
	v_mfma_f32_16x16x32_bf16 v[76:79], v[174:177], v[198:201], v[76:79]
	v_mfma_f32_16x16x32_bf16 v[68:71], v[166:169], v[206:209], v[68:71]
	v_mfma_f32_16x16x32_bf16 v[64:67], v[174:177], v[206:209], v[64:67]
	v_mfma_f32_16x16x32_bf16 v[116:119], v[170:173], v[186:189], v[116:119]
	v_mfma_f32_16x16x32_bf16 v[108:111], v[178:181], v[186:189], v[108:111]
	v_mfma_f32_16x16x32_bf16 v[100:103], v[170:173], v[194:197], v[100:103]
	v_mfma_f32_16x16x32_bf16 v[92:95], v[178:181], v[194:197], v[92:95]
	v_mfma_f32_16x16x32_bf16 v[84:87], v[170:173], v[202:205], v[84:87]
	v_mfma_f32_16x16x32_bf16 v[76:79], v[178:181], v[202:205], v[76:79]
	v_mfma_f32_16x16x32_bf16 v[68:71], v[170:173], v[210:213], v[68:71]
	v_mfma_f32_16x16x32_bf16 v[64:67], v[178:181], v[210:213], v[64:67]
	s_setprio 0
	s_waitcnt vmcnt(16)
	s_barrier
	s_add_i32 s61, s49, s40
	v_lshl_add_u64 v[142:143], s[34:35], 0, v[132:133]
	s_mov_b32 m0, s61
	ds_read_b128 v[182:185], v149 offset:16384
	ds_read_b128 v[186:189], v149 offset:17408
	ds_read_b128 v[190:193], v149 offset:18432
	ds_read_b128 v[194:197], v149 offset:19456
	ds_read_b128 v[198:201], v149 offset:20480
	ds_read_b128 v[202:205], v149 offset:21504
	ds_read_b128 v[206:209], v149 offset:22528
	ds_read_b128 v[210:213], v149 offset:23552
	s_cbranch_vccz .Ldl_2
	global_load_lds_dwordx4 v[142:143], off
	v_lshl_add_u64 v[142:143], v[142:143], 0, s[68:69]
	s_add_i32 m0, m0, 0x1000
	s_nop 0
	global_load_lds_dwordx4 v[142:143], off
	v_lshl_add_u64 v[142:143], v[142:143], 0, s[70:71]
.Ldl_2:
	s_add_i32 m0, s61, 0x2000
	s_add_u32 s62, s34, 0x100000
	v_lshl_add_u64 v[214:215], s[34:35], 0, v[128:129]
	s_addc_u32 s63, s35, 0
	s_add_i32 s61, s50, s40
	s_cbranch_vccz .Ldl_3
	global_load_lds_dwordx4 v[214:215], off
	v_lshl_add_u64 v[214:215], v[214:215], 0, s[68:69]
	s_add_i32 m0, m0, 0x1000
	s_nop 0
	global_load_lds_dwordx4 v[214:215], off
	v_lshl_add_u64 v[214:215], v[214:215], 0, s[70:71]
.Ldl_3:
	v_lshl_add_u64 v[216:217], s[62:63], 0, v[132:133]
	s_mov_b32 m0, s61
	v_lshl_add_u64 v[218:219], s[36:37], 0, v[130:131]
	s_cbranch_vccz .Ldl_4
	global_load_lds_dwordx4 v[216:217], off
	v_lshl_add_u64 v[216:217], v[216:217], 0, s[68:69]
	s_add_i32 m0, m0, 0x1000
	s_nop 0
	global_load_lds_dwordx4 v[216:217], off
	v_lshl_add_u64 v[216:217], v[216:217], 0, s[70:71]
.Ldl_4:
	v_lshl_add_u64 v[216:217], s[62:63], 0, v[128:129]
	s_add_i32 m0, s61, 0x2000
	s_nop 0
	s_cbranch_vccz .Ldl_5
	global_load_lds_dwordx4 v[216:217], off
	v_lshl_add_u64 v[216:217], v[216:217], 0, s[68:69]
	s_add_i32 m0, m0, 0x1000
	s_nop 0
	global_load_lds_dwordx4 v[216:217], off
	v_lshl_add_u64 v[216:217], v[216:217], 0, s[70:71]
.Ldl_5:
	v_lshl_add_u64 v[216:217], s[36:37], 0, v[134:135]
	s_mov_b32 m0, s29
	s_nop 0
	s_cbranch_vccz .Ldl_6
	global_load_lds_dwordx4 v[216:217], off
	v_lshl_add_u64 v[216:217], v[216:217], 0, s[68:69]
	s_add_i32 m0, m0, 0x1000
	s_nop 0
	global_load_lds_dwordx4 v[216:217], off
	v_lshl_add_u64 v[216:217], v[216:217], 0, s[70:71]
.Ldl_6:
	s_mov_b32 m0, s43
	s_nop 0
	s_cbranch_vccz .Ldl_7
	global_load_lds_dwordx4 v[218:219], off
	v_lshl_add_u64 v[218:219], v[218:219], 0, s[68:69]
	s_add_i32 m0, m0, 0x1000
	s_nop 0
	global_load_lds_dwordx4 v[218:219], off
	v_lshl_add_u64 v[218:219], v[218:219], 0, s[70:71]

; #define PG8_STAGE(bufoff, gbase, voff) do { _Pragma("unroll") for (int _i = 0; _i < 2; ++_i) \
;         __builtin_amdgcn_global_load_lds((const unsigned*)((const char*)(gbase) + (voff)[_i]), (PG8_LAS unsigned*)(lds + (bufoff) + ldsw + _i * 8192), 16, 0, 0); } while (0)
; #define PG8_LDA(dst, b, h) do { _Pragma("unroll") for (int m = 0; m < 4; ++m) _Pragma("unroll") for (int k = 0; k < 2; ++k) dst[m][k] = *(const PG8_LAS bf16x8*)(lds + PG8_SA(b, h) + aoff + m * 2048 + k * 1024); } while (0)
; #define PG8_LDB(dst, b, h) do { _Pragma("unroll") for (int n = 0; n < 2; ++n) _Pragma("unroll") for (int k = 0; k < 2; ++k) dst[n][k] = *(const PG8_LAS bf16x8*)(lds + PG8_SB(b, h) + boff + n * 2048 + k * 1024); } while (0)
; #define PG8_MMA(ai, bj, At, Bt) do { __builtin_amdgcn_s_setprio(1); _Pragma("unroll") for (int m = 0; m < 4; ++m) _Pragma("unroll") for (int n = 0; n < 2; ++n) _Pragma("unroll") for (int k = 0; k < 2; ++k) \
;         acc[ai][bj][m][n] = __builtin_amdgcn_mfma_f32_16x16x32_bf16(Bt[n][k], At[m][k], acc[ai][bj][m][n], 0, 0, 0); __builtin_amdgcn_s_setprio(0); } while (0)
; #define PG8_WAIT_V(n) asm volatile("s_waitcnt vmcnt(" #n ")" ::: "memory")
; #define PG8_WAIT_L(n) asm volatile("s_waitcnt lgkmcnt(" #n ")" ::: "memory")
; #define PG8_BAR __builtin_amdgcn_s_barrier()
; #define PG8_SCHED __builtin_amdgcn_sched_barrier(0)
; template <class Epi, class Sched, bool ALIGN_EPI = false, bool SP2 = false>
; __device__ __forceinline__ void gemm_phase(PG8_LAS unsigned char* lds, const Gemm g, const Sched& S, const Epi& E, int tid_in) {
;     ...
;             PG8_WAIT_V(8); PG8_WAIT_L(0); PG8_BAR; PG8_MMA(1, 0, At, B0); PG8_MMA(1, 1, At, B1); PG8_BAR; PG8_SCHED;
;             PG8_LDB(B0, 1, 0); PG8_LDB(B1, 1, 1); PG8_SCHED; PG8_LDA(At, 1, 0); PG8_STAGE(PG8_SA(0, 1), a2 + hstep, voffA);
;             PG8_WAIT_V(8); PG8_WAIT_L(0); PG8_BAR; PG8_MMA(0, 0, At, B0); PG8_MMA(0, 1, At, B1); PG8_BAR; PG8_SCHED;
.Ldw_1:
	s_waitcnt lgkmcnt(0)
	s_barrier
	s_setprio 1
	s_waitcnt lgkmcnt(0)
	v_mfma_f32_16x16x32_bf16 v[60:63], v[150:153], v[182:185], v[60:63]
	v_mfma_f32_16x16x32_bf16 v[56:59], v[158:161], v[182:185], v[56:59]
	v_mfma_f32_16x16x32_bf16 v[48:51], v[150:153], v[190:193], v[48:51]
	v_mfma_f32_16x16x32_bf16 v[40:43], v[158:161], v[190:193], v[40:43]
	v_mfma_f32_16x16x32_bf16 v[32:35], v[150:153], v[198:201], v[32:35]
	v_mfma_f32_16x16x32_bf16 v[24:27], v[158:161], v[198:201], v[24:27]
	v_mfma_f32_16x16x32_bf16 v[16:19], v[150:153], v[206:209], v[16:19]
	v_mfma_f32_16x16x32_bf16 v[8:11], v[158:161], v[206:209], v[8:11]
	v_mfma_f32_16x16x32_bf16 v[60:63], v[154:157], v[186:189], v[60:63]
	v_mfma_f32_16x16x32_bf16 v[56:59], v[162:165], v[186:189], v[56:59]
	v_mfma_f32_16x16x32_bf16 v[48:51], v[154:157], v[194:197], v[48:51]
	v_mfma_f32_16x16x32_bf16 v[40:43], v[162:165], v[194:197], v[40:43]
	v_mfma_f32_16x16x32_bf16 v[32:35], v[154:157], v[202:205], v[32:35]
	v_mfma_f32_16x16x32_bf16 v[24:27], v[162:165], v[202:205], v[24:27]
	v_mfma_f32_16x16x32_bf16 v[16:19], v[154:157], v[210:213], v[16:19]
	v_mfma_f32_16x16x32_bf16 v[8:11], v[162:165], v[210:213], v[8:11]
	s_setprio 0
	s_setprio 1
	v_mfma_f32_16x16x32_bf16 v[52:55], v[166:169], v[182:185], v[52:55]
	v_mfma_f32_16x16x32_bf16 v[44:47], v[174:177], v[182:185], v[44:47]
	v_mfma_f32_16x16x32_bf16 v[36:39], v[166:169], v[190:193], v[36:39]
	v_mfma_f32_16x16x32_bf16 v[28:31], v[174:177], v[190:193], v[28:31]
	v_mfma_f32_16x16x32_bf16 v[20:23], v[166:169], v[198:201], v[20:23]
	v_mfma_f32_16x16x32_bf16 v[12:15], v[174:177], v[198:201], v[12:15]
	v_mfma_f32_16x16x32_bf16 v[4:7], v[166:169], v[206:209], v[4:7]
	v_mfma_f32_16x16x32_bf16 v[0:3], v[174:177], v[206:209], v[0:3]
	v_mfma_f32_16x16x32_bf16 v[52:55], v[170:173], v[186:189], v[52:55]
	v_mfma_f32_16x16x32_bf16 v[44:47], v[178:181], v[186:189], v[44:47]
	v_mfma_f32_16x16x32_bf16 v[36:39], v[170:173], v[194:197], v[36:39]
	v_mfma_f32_16x16x32_bf16 v[28:31], v[178:181], v[194:197], v[28:31]
	v_mfma_f32_16x16x32_bf16 v[20:23], v[170:173], v[202:205], v[20:23]
	v_mfma_f32_16x16x32_bf16 v[12:15], v[178:181], v[202:205], v[12:15]
	v_mfma_f32_16x16x32_bf16 v[4:7], v[170:173], v[210:213], v[4:7]
	v_mfma_f32_16x16x32_bf16 v[0:3], v[178:181], v[210:213], v[0:3]
	s_setprio 0
	s_waitcnt vmcnt(16)
	s_barrier
	s_add_i32 s61, 0, 0x18000
	s_add_i32 s62, 0, 0x1c000
	v_add_u32_e32 v162, s61, v145
	v_add_u32_e32 v178, s62, v145
	ds_read_b128 v[150:153], v162
	ds_read_b128 v[154:157], v162 offset:1024
	ds_read_b128 v[158:161], v162 offset:2048
	ds_read_b128 v[162:165], v162 offset:3072
	ds_read_b128 v[166:169], v178
	ds_read_b128 v[170:173], v178 offset:1024
	ds_read_b128 v[174:177], v178 offset:2048
	ds_read_b128 v[178:181], v178 offset:3072
	s_add_u32 s36, s36, 0x100000
	s_addc_u32 s37, s37, 0
	s_mov_b32 m0, s44
	v_lshl_add_u64 v[220:221], s[36:37], 0, v[134:135]
	ds_read_b128 v[182:185], v149 offset:32768
	ds_read_b128 v[186:189], v149 offset:33792
	ds_read_b128 v[190:193], v149 offset:34816
	ds_read_b128 v[194:197], v149 offset:35840
	ds_read_b128 v[198:201], v149 offset:36864
	ds_read_b128 v[202:205], v149 offset:37888
	ds_read_b128 v[206:209], v149 offset:38912
	ds_read_b128 v[210:213], v149 offset:39936
	s_cbranch_vccz .Ldl_8
	global_load_lds_dwordx4 v[220:221], off
	v_lshl_add_u64 v[220:221], v[220:221], 0, s[68:69]
	s_add_i32 m0, m0, 0x1000
	s_nop 0
	global_load_lds_dwordx4 v[220:221], off
	v_lshl_add_u64 v[220:221], v[220:221], 0, s[70:71]
.Ldl_8:
	v_lshl_add_u64 v[220:221], s[36:37], 0, v[130:131]
	s_mov_b32 m0, s45
	s_nop 0
	s_cbranch_vccz .Ldl_9
	global_load_lds_dwordx4 v[220:221], off
	v_lshl_add_u64 v[220:221], v[220:221], 0, s[68:69]
	s_add_i32 m0, m0, 0x1000
	s_nop 0
	global_load_lds_dwordx4 v[220:221], off
	v_lshl_add_u64 v[220:221], v[220:221], 0, s[70:71]

; #define PG8_STAGE(bufoff, gbase, voff) do { _Pragma("unroll") for (int _i = 0; _i < 2; ++_i) \
;         __builtin_amdgcn_global_load_lds((const unsigned*)((const char*)(gbase) + (voff)[_i]), (PG8_LAS unsigned*)(lds + (bufoff) + ldsw + _i * 8192), 16, 0, 0); } while (0)
; #define PG8_LDA(dst, b, h) do { _Pragma("unroll") for (int m = 0; m < 4; ++m) _Pragma("unroll") for (int k = 0; k < 2; ++k) dst[m][k] = *(const PG8_LAS bf16x8*)(lds + PG8_SA(b, h) + aoff + m * 2048 + k * 1024); } while (0)
; #define PG8_MMA(ai, bj, At, Bt) do { __builtin_amdgcn_s_setprio(1); _Pragma("unroll") for (int m = 0; m < 4; ++m) _Pragma("unroll") for (int n = 0; n < 2; ++n) _Pragma("unroll") for (int k = 0; k < 2; ++k) \
;         acc[ai][bj][m][n] = __builtin_amdgcn_mfma_f32_16x16x32_bf16(Bt[n][k], At[m][k], acc[ai][bj][m][n], 0, 0, 0); __builtin_amdgcn_s_setprio(0); } while (0)
; #define PG8_WAIT_V(n) asm volatile("s_waitcnt vmcnt(" #n ")" ::: "memory")
; #define PG8_WAIT_L(n) asm volatile("s_waitcnt lgkmcnt(" #n ")" ::: "memory")
; #define PG8_BAR __builtin_amdgcn_s_barrier()
; #define PG8_SCHED __builtin_amdgcn_sched_barrier(0)
; template <class Epi, class Sched, bool ALIGN_EPI = false, bool SP2 = false>
; __device__ __forceinline__ void gemm_phase(PG8_LAS unsigned char* lds, const Gemm g, const Sched& S, const Epi& E, int tid_in) {
;     ...
;             PG8_WAIT_V(8); PG8_WAIT_L(0); PG8_BAR; PG8_MMA(0, 0, At, B0); PG8_MMA(0, 1, At, B1); PG8_BAR; PG8_SCHED;
;             PG8_LDA(At, 1, 1); PG8_STAGE(PG8_SB(1, 0), b3, voffB); PG8_STAGE(PG8_SB(1, 1), b3 + hstep, voffB); PG8_STAGE(PG8_SA(1, 0), a3, voffA);
;             PG8_WAIT_V(8); PG8_WAIT_L(0); PG8_BAR; PG8_MMA(1, 0, At, B0); PG8_MMA(1, 1, At, B1); PG8_BAR; PG8_SCHED;
.Ldw_2:
	s_waitcnt lgkmcnt(0)
	s_barrier
	s_setprio 1
	s_waitcnt lgkmcnt(0)
	v_mfma_f32_16x16x32_bf16 v[124:127], v[150:153], v[182:185], v[124:127]
	v_mfma_f32_16x16x32_bf16 v[120:123], v[158:161], v[182:185], v[120:123]
	v_mfma_f32_16x16x32_bf16 v[112:115], v[150:153], v[190:193], v[112:115]
	v_mfma_f32_16x16x32_bf16 v[104:107], v[158:161], v[190:193], v[104:107]
	v_mfma_f32_16x16x32_bf16 v[96:99], v[150:153], v[198:201], v[96:99]
	v_mfma_f32_16x16x32_bf16 v[88:91], v[158:161], v[198:201], v[88:91]
	v_mfma_f32_16x16x32_bf16 v[80:83], v[150:153], v[206:209], v[80:83]
	v_mfma_f32_16x16x32_bf16 v[72:75], v[158:161], v[206:209], v[72:75]
	v_mfma_f32_16x16x32_bf16 v[124:127], v[154:157], v[186:189], v[124:127]
	v_mfma_f32_16x16x32_bf16 v[120:123], v[162:165], v[186:189], v[120:123]
	v_mfma_f32_16x16x32_bf16 v[112:115], v[154:157], v[194:197], v[112:115]
	v_mfma_f32_16x16x32_bf16 v[104:107], v[162:165], v[194:197], v[104:107]
	v_mfma_f32_16x16x32_bf16 v[96:99], v[154:157], v[202:205], v[96:99]
	v_mfma_f32_16x16x32_bf16 v[88:91], v[162:165], v[202:205], v[88:91]
	v_mfma_f32_16x16x32_bf16 v[80:83], v[154:157], v[210:213], v[80:83]
	v_mfma_f32_16x16x32_bf16 v[72:75], v[162:165], v[210:213], v[72:75]
	s_setprio 0
	s_setprio 1
	v_mfma_f32_16x16x32_bf16 v[116:119], v[166:169], v[182:185], v[116:119]
	v_mfma_f32_16x16x32_bf16 v[108:111], v[174:177], v[182:185], v[108:111]
	v_mfma_f32_16x16x32_bf16 v[100:103], v[166:169], v[190:193], v[100:103]
	v_mfma_f32_16x16x32_bf16 v[92:95], v[174:177], v[190:193], v[92:95]
	v_mfma_f32_16x16x32_bf16 v[84:87], v[166:169], v[198:201], v[84:87]
	v_mfma_f32_16x16x32_bf16 v[76:79], v[174:177], v[198:201], v[76:79]
	v_mfma_f32_16x16x32_bf16 v[68:71], v[166:169], v[206:209], v[68:71]
	v_mfma_f32_16x16x32_bf16 v[64:67], v[174:177], v[206:209], v[64:67]
	v_mfma_f32_16x16x32_bf16 v[116:119], v[170:173], v[186:189], v[116:119]
	v_mfma_f32_16x16x32_bf16 v[108:111], v[178:181], v[186:189], v[108:111]
	v_mfma_f32_16x16x32_bf16 v[100:103], v[170:173], v[194:197], v[100:103]
	v_mfma_f32_16x16x32_bf16 v[92:95], v[178:181], v[194:197], v[92:95]
	v_mfma_f32_16x16x32_bf16 v[84:87], v[170:173], v[202:205], v[84:87]
	v_mfma_f32_16x16x32_bf16 v[76:79], v[178:181], v[202:205], v[76:79]
	v_mfma_f32_16x16x32_bf16 v[68:71], v[170:173], v[210:213], v[68:71]
	v_mfma_f32_16x16x32_bf16 v[64:67], v[178:181], v[210:213], v[64:67]
	s_setprio 0
	s_waitcnt vmcnt(16)
	s_barrier
	s_add_i32 s36, s61, s40
	v_lshl_add_u64 v[142:143], v[142:143], 0, s[6:7]
	s_mov_b32 m0, s36
	ds_read_b128 v[182:185], v149 offset:49152
	ds_read_b128 v[186:189], v149 offset:50176
	ds_read_b128 v[190:193], v149 offset:51200
	ds_read_b128 v[194:197], v149 offset:52224
	ds_read_b128 v[198:201], v149 offset:53248
	ds_read_b128 v[202:205], v149 offset:54272
	ds_read_b128 v[206:209], v149 offset:55296
	ds_read_b128 v[210:213], v149 offset:56320
	s_cbranch_vccz .Ldl_10
	global_load_lds_dwordx4 v[142:143], off
	v_lshl_add_u64 v[142:143], v[142:143], 0, s[68:69]
	s_add_i32 m0, m0, 0x1000
	s_nop 0
	global_load_lds_dwordx4 v[142:143], off
	v_lshl_add_u64 v[142:143], v[142:143], 0, s[70:71]
.Ldl_10:
	s_add_i32 m0, s36, 0x2000
	s_add_u32 s34, s34, 0x100080
	v_lshl_add_u64 v[142:143], v[214:215], 0, s[6:7]
	s_addc_u32 s35, s35, 0
	s_add_i32 s36, s62, s40
	s_cbranch_vccz .Ldl_11
	global_load_lds_dwordx4 v[142:143], off
	v_lshl_add_u64 v[142:143], v[142:143], 0, s[68:69]
	s_add_i32 m0, m0, 0x1000
	s_nop 0
	global_load_lds_dwordx4 v[142:143], off
	v_lshl_add_u64 v[142:143], v[142:143], 0, s[70:71]
.Ldl_11:
	v_lshl_add_u64 v[142:143], s[34:35], 0, v[132:133]
	s_mov_b32 m0, s36
	s_nop 0
	s_cbranch_vccz .Ldl_12
	global_load_lds_dwordx4 v[142:143], off
	v_lshl_add_u64 v[142:143], v[142:143], 0, s[68:69]
	s_add_i32 m0, m0, 0x1000
	s_nop 0
	global_load_lds_dwordx4 v[142:143], off
	v_lshl_add_u64 v[142:143], v[142:143], 0, s[70:71]
.Ldl_12:
	v_lshl_add_u64 v[142:143], s[34:35], 0, v[128:129]
	s_add_i32 m0, s36, 0x2000
	s_nop 0
	s_cbranch_vccz .Ldl_13
	global_load_lds_dwordx4 v[142:143], off
	v_lshl_add_u64 v[142:143], v[142:143], 0, s[68:69]
	s_add_i32 m0, m0, 0x1000
	s_nop 0
	global_load_lds_dwordx4 v[142:143], off
	v_lshl_add_u64 v[142:143], v[142:143], 0, s[70:71]
.Ldl_13:
	v_lshl_add_u64 v[142:143], v[216:217], 0, s[6:7]
	s_mov_b32 m0, s47
	s_nop 0
	s_cbranch_vccz .Ldl_14
	global_load_lds_dwordx4 v[142:143], off
	v_lshl_add_u64 v[142:143], v[142:143], 0, s[68:69]
	s_add_i32 m0, m0, 0x1000
	s_nop 0
	global_load_lds_dwordx4 v[142:143], off
	v_lshl_add_u64 v[142:143], v[142:143], 0, s[70:71]
.Ldl_14:
	v_lshl_add_u64 v[142:143], v[218:219], 0, s[6:7]
	s_mov_b32 m0, s48
	s_nop 0
	s_cbranch_vccz .Ldl_15
	global_load_lds_dwordx4 v[142:143], off
	v_lshl_add_u64 v[142:143], v[142:143], 0, s[68:69]
	s_add_i32 m0, m0, 0x1000
	s_nop 0
	global_load_lds_dwordx4 v[142:143], off
	v_lshl_add_u64 v[142:143], v[142:143], 0, s[70:71]

; #define PG8_STAGE(bufoff, gbase, voff) do { _Pragma("unroll") for (int _i = 0; _i < 2; ++_i) \
;         __builtin_amdgcn_global_load_lds((const unsigned*)((const char*)(gbase) + (voff)[_i]), (PG8_LAS unsigned*)(lds + (bufoff) + ldsw + _i * 8192), 16, 0, 0); } while (0)
; #define PG8_LDA(dst, b, h) do { _Pragma("unroll") for (int m = 0; m < 4; ++m) _Pragma("unroll") for (int k = 0; k < 2; ++k) dst[m][k] = *(const PG8_LAS bf16x8*)(lds + PG8_SA(b, h) + aoff + m * 2048 + k * 1024); } while (0)
; #define PG8_MMA(ai, bj, At, Bt) do { __builtin_amdgcn_s_setprio(1); _Pragma("unroll") for (int m = 0; m < 4; ++m) _Pragma("unroll") for (int n = 0; n < 2; ++n) _Pragma("unroll") for (int k = 0; k < 2; ++k) \
;         acc[ai][bj][m][n] = __builtin_amdgcn_mfma_f32_16x16x32_bf16(Bt[n][k], At[m][k], acc[ai][bj][m][n], 0, 0, 0); __builtin_amdgcn_s_setprio(0); } while (0)
; #define PG8_WAIT_V(n) asm volatile("s_waitcnt vmcnt(" #n ")" ::: "memory")
; #define PG8_WAIT_L(n) asm volatile("s_waitcnt lgkmcnt(" #n ")" ::: "memory")
; #define PG8_BAR __builtin_amdgcn_s_barrier()
; #define PG8_SCHED __builtin_amdgcn_sched_barrier(0)
; template <class Epi, class Sched, bool ALIGN_EPI = false, bool SP2 = false>
; __device__ __forceinline__ void gemm_phase(PG8_LAS unsigned char* lds, const Gemm g, const Sched& S, const Epi& E, int tid_in) {
;     ...
;             PG8_WAIT_V(8); PG8_WAIT_L(0); PG8_BAR; PG8_MMA(0, 0, At, B0); PG8_MMA(0, 1, At, B1); PG8_BAR; PG8_SCHED;
;             PG8_LDA(At, 1, 1); PG8_STAGE(PG8_SB(1, 0), b3, voffB); PG8_STAGE(PG8_SB(1, 1), b3 + hstep, voffB); PG8_STAGE(PG8_SA(1, 0), a3, voffA);
;             PG8_WAIT_V(8); PG8_WAIT_L(0); PG8_BAR; PG8_MMA(1, 0, At, B0); PG8_MMA(1, 1, At, B1); PG8_BAR; PG8_SCHED;
.Ldw_3:
	s_waitcnt lgkmcnt(0)
	s_barrier
	s_setprio 1
	s_waitcnt lgkmcnt(0)
	v_mfma_f32_16x16x32_bf16 v[60:63], v[150:153], v[182:185], v[60:63]
	v_mfma_f32_16x16x32_bf16 v[56:59], v[158:161], v[182:185], v[56:59]
	v_mfma_f32_16x16x32_bf16 v[48:51], v[150:153], v[190:193], v[48:51]
	v_mfma_f32_16x16x32_bf16 v[40:43], v[158:161], v[190:193], v[40:43]
	v_mfma_f32_16x16x32_bf16 v[32:35], v[150:153], v[198:201], v[32:35]
	v_mfma_f32_16x16x32_bf16 v[24:27], v[158:161], v[198:201], v[24:27]
	v_mfma_f32_16x16x32_bf16 v[16:19], v[150:153], v[206:209], v[16:19]
	v_mfma_f32_16x16x32_bf16 v[8:11], v[158:161], v[206:209], v[8:11]
	v_mfma_f32_16x16x32_bf16 v[60:63], v[154:157], v[186:189], v[60:63]
	v_mfma_f32_16x16x32_bf16 v[56:59], v[162:165], v[186:189], v[56:59]
	v_mfma_f32_16x16x32_bf16 v[48:51], v[154:157], v[194:197], v[48:51]
	v_mfma_f32_16x16x32_bf16 v[40:43], v[162:165], v[194:197], v[40:43]
	v_mfma_f32_16x16x32_bf16 v[32:35], v[154:157], v[202:205], v[32:35]
	v_mfma_f32_16x16x32_bf16 v[24:27], v[162:165], v[202:205], v[24:27]
	v_mfma_f32_16x16x32_bf16 v[16:19], v[154:157], v[210:213], v[16:19]
	v_mfma_f32_16x16x32_bf16 v[8:11], v[162:165], v[210:213], v[8:11]
	s_setprio 0
	s_setprio 1
	v_mfma_f32_16x16x32_bf16 v[52:55], v[166:169], v[182:185], v[52:55]
	v_mfma_f32_16x16x32_bf16 v[44:47], v[174:177], v[182:185], v[44:47]
	v_mfma_f32_16x16x32_bf16 v[36:39], v[166:169], v[190:193], v[36:39]
	v_mfma_f32_16x16x32_bf16 v[28:31], v[174:177], v[190:193], v[28:31]
	v_mfma_f32_16x16x32_bf16 v[20:23], v[166:169], v[198:201], v[20:23]
	v_mfma_f32_16x16x32_bf16 v[12:15], v[174:177], v[198:201], v[12:15]
	v_mfma_f32_16x16x32_bf16 v[4:7], v[166:169], v[206:209], v[4:7]
	v_mfma_f32_16x16x32_bf16 v[0:3], v[174:177], v[206:209], v[0:3]
	v_mfma_f32_16x16x32_bf16 v[52:55], v[170:173], v[186:189], v[52:55]
	v_mfma_f32_16x16x32_bf16 v[44:47], v[178:181], v[186:189], v[44:47]
	v_mfma_f32_16x16x32_bf16 v[36:39], v[170:173], v[194:197], v[36:39]
	v_mfma_f32_16x16x32_bf16 v[28:31], v[178:181], v[194:197], v[28:31]
	v_mfma_f32_16x16x32_bf16 v[20:23], v[170:173], v[202:205], v[20:23]
	v_mfma_f32_16x16x32_bf16 v[12:15], v[178:181], v[202:205], v[12:15]
	v_mfma_f32_16x16x32_bf16 v[4:7], v[170:173], v[210:213], v[4:7]
	v_mfma_f32_16x16x32_bf16 v[0:3], v[178:181], v[210:213], v[0:3]
	s_setprio 0
	s_waitcnt vmcnt(16)
	s_barrier
	s_add_i32 s60, s60, 2
	s_add_u32 s30, s30, 0x100
	s_addc_u32 s31, s31, 0
	s_add_u32 s58, s58, 0x100
	s_addc_u32 s59, s59, 0
	s_cmp_gt_u32 s60, 61
	s_cbranch_scc0 .LBB0_1551
	s_and_b64 vcc, exec, s[8:9]
	s_cbranch_vccz .LBB0_1554
	s_barrier
